# GEMM-side flag wait trimmed: one release barrier instead of two, partial-counter gather skipped on the up-GEMM path
# speedup vs baseline: 1.0006x; 1.0006x over previous
.LBB0_388:
	s_or_b64 exec, exec, s[4:5]
	s_cmp_eq_u32 s51, 1
	s_mov_b64 s[4:5], -1
	s_cmp_lg_u32 s86, 0
	s_cbranch_scc1 .Lhf_done
	s_load_dwordx2 s[6:7], s[66:67], 0x100
	v_mov_b32_e32 v0, 0x2017c
	ds_read_b32 v2, v0
	v_readlane_b32 s0, v255, 0
	s_nop 3
	s_and_b32 s1, s0, 7
	s_lshr_b32 s2, s0, 3
	s_cmp_eq_u32 s51, 1
	s_cbranch_scc1 .Lhf_in
	s_mul_i32 s3, s1, 88
	s_add_i32 s3, s3, s2
	s_mul_i32 s8, s3, 0x5d18
	s_lshr_b32 s8, s8, 22
	s_mul_i32 s14, s8, 0xb0
	s_sub_i32 s14, s3, s14
	s_and_b32 s14, s14, 7
	s_lshl_b32 s8, s8, 3
	s_add_i32 s8, s8, s14
	s_add_i32 s15, s3, 32
	s_mul_i32 s9, s15, 0x5d18
	s_lshr_b32 s9, s9, 22
	s_mul_i32 s14, s9, 0xb0
	s_sub_i32 s14, s15, s14
	s_and_b32 s14, s14, 7
	s_lshl_b32 s9, s9, 3
	s_add_i32 s9, s9, s14
	s_add_i32 s15, s3, 64
	s_cmp_lt_u32 s0, 0xc0
	s_cselect_b32 s15, s15, s3
	s_mul_i32 s10, s15, 0x5d18
	s_lshr_b32 s10, s10, 22
	s_mul_i32 s14, s10, 0xb0
	s_sub_i32 s14, s15, s14
	s_and_b32 s14, s14, 7
	s_lshl_b32 s10, s10, 3
	s_add_i32 s10, s10, s14
	v_mov_b32_e32 v9, 0
	s_mov_b32 s11, 0
	s_branch .Lhf_poll
.Lhf_in:
	s_mov_b32 s11, 1
	s_lshl_b32 s8, s1, 2
	s_and_b32 s2, s2, 3
	s_add_i32 s8, s8, s2
	s_mov_b32 s9, s8
	s_mov_b32 s10, s8
	v_mov_b32_e32 v9, 0x20178
	ds_read_b32 v9, v9

.Lhf_loop:
	global_load_dword v6, v3, s[6:7] sc1
	global_load_dword v7, v4, s[6:7] sc1
	global_load_dword v8, v5, s[6:7] sc1
	s_cmp_eq_u32 s11, 0
	s_cbranch_scc1 .Lhf_nop
	global_load_dword v11, v10, s[6:7] sc1
.Lhf_nop:
	s_waitcnt vmcnt(0)
	v_min3_u32 v6, v6, v7, v8
	v_cmp_le_u32_e32 vcc, v2, v6
	s_nop 4
	s_cbranch_vccz .Lhf_slp
	s_cmp_eq_u32 s11, 0
	s_cbranch_scc1 .Lhf_rel
	v_cmp_le_u32_e32 vcc, v9, v11
	s_nop 1
	s_andn2_b64 s[0:1], exec, vcc
	s_cbranch_scc0 .Lhf_rel

.Lhf_done:
	s_waitcnt lgkmcnt(0)
	s_barrier
	s_cmp_eq_u32 s51, 1
	s_cbranch_scc1 .LBB0_408
	s_mov_b64 s[8:9], s[66:67]
	v_mov_b32_e32 v0, v1
	s_load_dwordx2 s[10:11], s[8:9], 0x100
	v_mbcnt_lo_u32_b32 v0, -1, v0
	v_mbcnt_hi_u32_b32 v144, -1, v0
	v_readlane_b32 s0, v254, 8
	v_add_u32_e32 v0, s86, v144
	v_readlane_b32 s1, v254, 9
	s_lshr_b32 s52, s51, 1
	v_readfirstlane_b32 s4, v0
	s_andn2_b64 vcc, exec, s[0:1]
	v_readlane_b32 s0, v255, 16
	s_ashr_i32 s30, s4, 6
	s_add_i32 s52, s52, s0
	s_cbranch_vccnz .LBB0_410
	v_lshlrev_b32_e32 v2, 4, v0
	v_add_u32_e32 v3, 0x2000, v2
	v_ashrrev_i32_e32 v4, 31, v3
	v_lshrrev_b32_e32 v4, 22, v4
	v_add_u32_e32 v4, v3, v4
	v_ashrrev_i32_e32 v10, 10, v4
	v_mul_i32_i24_e32 v4, 0x400, v10
	v_sub_u32_e32 v3, v3, v4
	v_lshrrev_b32_e32 v4, 4, v3
	v_bitop3_b32 v3, v4, v3, 32 bitop3:0x6c
	v_ashrrev_i32_e32 v4, 31, v3
	v_lshrrev_b32_e32 v4, 26, v4
	v_add_u32_e32 v4, v3, v4
	v_lshlrev_b32_e32 v5, 3, v10
	v_ashrrev_i32_e32 v11, 6, v4
	v_and_b32_e32 v5, -16, v5
	v_add_u32_e32 v5, v11, v5
	v_and_b32_e32 v6, 3, v11
	s_mov_b32 s6, 0x1fffe0
	v_lshrrev_b32_e32 v7, 2, v5
	v_lshlrev_b32_e32 v8, 1, v5
	v_and_b32_e32 v4, 0xc0, v4
	v_and_or_b32 v6, v5, s6, v6
	v_and_b32_e32 v7, 4, v7
	v_and_b32_e32 v8, 24, v8
	v_sub_u32_e32 v3, v3, v4
	v_or3_b32 v6, v6, v7, v8
	v_lshlrev_b32_e32 v7, 5, v10
	v_ashrrev_i16_sdwa v3, v236, sext(v3) dst_sel:DWORD dst_unused:UNUSED_PAD src0_sel:DWORD src1_sel:BYTE_0
	v_and_b32_e32 v7, 32, v7
	v_bfe_i32 v12, v3, 0, 16
	v_add_lshl_u32 v3, v7, v12, 1
	v_lshl_add_u32 v130, v6, 11, v3
	v_lshl_add_u32 v132, v5, 11, v3
	v_bfe_i32 v3, v0, 27, 1
	v_lshrrev_b32_e32 v3, 22, v3
	v_add_u32_e32 v3, v2, v3
	v_and_b32_e32 v3, 0xfffffc00, v3
	v_sub_u32_e32 v2, v2, v3
	v_lshrrev_b32_e32 v3, 4, v2
	v_ashrrev_i32_e32 v4, 31, v0
	v_bitop3_b32 v2, v3, v2, 32 bitop3:0x6c
	v_lshrrev_b32_e32 v4, 26, v4
	v_ashrrev_i32_e32 v3, 31, v2
	v_add_u32_e32 v0, v0, v4
	v_lshrrev_b32_e32 v3, 26, v3
	v_ashrrev_i32_e32 v14, 6, v0
	v_add_u32_e32 v3, v2, v3
	v_lshlrev_b32_e32 v0, 3, v14
	v_ashrrev_i32_e32 v13, 6, v3
	v_and_b32_e32 v0, -16, v0
	s_waitcnt lgkmcnt(0)
	s_add_u32 s0, s10, 0x5c00000
	v_add_u32_e32 v4, v13, v0
	s_addc_u32 s1, s11, 0
	s_mul_i32 s2, s52, 0xb00000
	v_and_b32_e32 v0, 3, v13
	v_lshrrev_b32_e32 v5, 2, v4
	v_lshlrev_b32_e32 v6, 1, v4
	v_and_b32_e32 v3, 0xc0, v3
	s_mul_hi_u32 s3, s52, 0xb00000
	s_add_u32 s2, s10, s2
	v_and_or_b32 v0, v4, s6, v0
	v_and_b32_e32 v5, 4, v5
	v_and_b32_e32 v6, 24, v6
	v_sub_u32_e32 v2, v2, v3
	s_addc_u32 s3, s11, s3
	s_ashr_i32 s5, s4, 8
	s_lshl_b32 s31, s30, 10
	v_or3_b32 v0, v0, v5, v6
	v_lshlrev_b32_e32 v5, 5, v14
	v_ashrrev_i16_sdwa v2, v236, sext(v2) dst_sel:DWORD dst_unused:UNUSED_PAD src0_sel:DWORD src1_sel:BYTE_0
	v_readlane_b32 s6, v254, 15
	v_and_b32_e32 v5, 32, v5
	v_bfe_i32 v15, v2, 0, 16
	v_readlane_b32 s7, v254, 16
	s_add_u32 s24, s2, s6
	v_add_lshl_u32 v2, v5, v15, 1
	s_addc_u32 s25, s3, s7
	s_add_i32 s33, s31, 0
	v_lshl_add_u32 v0, v0, 11, v2
	s_add_i32 m0, s33, 0x10000
	v_readlane_b32 s6, v254, 13
	global_load_lds_dwordx4 v0, s[24:25]
	s_add_i32 m0, s33, 0x12000
	v_readlane_b32 s7, v254, 14
	s_add_u32 s26, s0, s6
	s_addc_u32 s27, s1, s7
	s_add_u32 s6, s24, 0x40000
	global_load_lds_dwordx4 v130, s[24:25]
	s_addc_u32 s7, s25, 0
	s_add_i32 m0, s33, 0x14000
	s_add_i32 s34, s33, 0x2000
	global_load_lds_dwordx4 v0, s[6:7]
	s_add_i32 m0, s33, 0x16000
	v_lshl_add_u32 v134, v4, 11, v2
	global_load_lds_dwordx4 v130, s[6:7]
	s_mov_b32 m0, s33
	s_add_u32 s6, s26, 0x40000
	global_load_lds_dwordx4 v134, s[26:27]
	s_mov_b32 m0, s34
	s_addc_u32 s7, s27, 0
	s_add_i32 s35, s33, 0x4000
	global_load_lds_dwordx4 v132, s[26:27]
	s_mov_b32 m0, s35
	s_add_i32 s36, s33, 0x6000
	global_load_lds_dwordx4 v134, s[6:7]
	s_mov_b32 m0, s36
	v_mov_b32_e32 v131, v1
	global_load_lds_dwordx4 v132, s[6:7]
	v_mov_b32_e32 v135, v1
	v_mov_b32_e32 v133, v1
	s_cmp_eq_u32 s5, 1
	v_lshl_add_u64 v[8:9], s[24:25], 0, v[0:1]
	v_lshl_add_u64 v[6:7], s[24:25], 0, v[130:131]
	v_lshl_add_u64 v[2:3], s[26:27], 0, v[134:135]
	s_cselect_b64 s[14:15], -1, 0
	s_cmp_lg_u32 s5, 1
	v_lshl_add_u64 v[4:5], s[26:27], 0, v[132:133]
	s_cbranch_scc1 .LBB0_392
	s_barrier
